# v087 with the 16 now-dead unit-header address adds removed
# baseline (speedup 1.0000x reference)
.LBB0_248:
	s_ashr_i32 s25, s24, 31
	s_lshl_b64 s[28:29], s[24:25], 19
	s_add_u32 s28, s43, s28
	s_addc_u32 s29, s44, s29
	s_and_b64 s[0:1], s[0:1], exec
	s_cselect_b32 s5, s29, s31
	s_cselect_b32 s25, s28, s30
	s_cmp_lg_u32 s34, 0
	s_cselect_b64 s[0:1], -1, 0
	s_add_u32 s78, s30, 0x100
	v_mov_b32_e32 v66, 0
	s_addc_u32 s79, s31, 0
	s_mov_b32 s80, -2
	s_mov_b64 s[30:31], 0
	v_mov_b32_e32 v67, v66
	v_mov_b32_e32 v68, v66
	v_mov_b32_e32 v69, v66
	v_mov_b32_e32 v70, v66
	v_mov_b32_e32 v71, v66
	v_mov_b32_e32 v72, v66
	v_mov_b32_e32 v73, v66
	v_mov_b32_e32 v82, v66
	v_mov_b32_e32 v83, v66
	v_mov_b32_e32 v84, v66
	v_mov_b32_e32 v85, v66
	v_mov_b32_e32 v86, v66
	v_mov_b32_e32 v87, v66
	v_mov_b32_e32 v88, v66
	v_mov_b32_e32 v89, v66
	v_mov_b32_e32 v98, v66
	v_mov_b32_e32 v99, v66
	v_mov_b32_e32 v100, v66
	v_mov_b32_e32 v101, v66
	v_mov_b32_e32 v102, v66
	v_mov_b32_e32 v103, v66
	v_mov_b32_e32 v104, v66
	v_mov_b32_e32 v105, v66
	v_mov_b32_e32 v114, v66
	v_mov_b32_e32 v115, v66
	v_mov_b32_e32 v116, v66
	v_mov_b32_e32 v117, v66
	v_mov_b32_e32 v118, v66
	v_mov_b32_e32 v119, v66
	v_mov_b32_e32 v120, v66
	v_mov_b32_e32 v121, v66
	v_mov_b32_e32 v74, v66
	v_mov_b32_e32 v75, v66
	v_mov_b32_e32 v76, v66
	v_mov_b32_e32 v77, v66
	v_mov_b32_e32 v78, v66
	v_mov_b32_e32 v79, v66
	v_mov_b32_e32 v80, v66
	v_mov_b32_e32 v81, v66
	v_mov_b32_e32 v90, v66
	v_mov_b32_e32 v91, v66
	v_mov_b32_e32 v92, v66
	v_mov_b32_e32 v93, v66
	v_mov_b32_e32 v94, v66
	v_mov_b32_e32 v95, v66
	v_mov_b32_e32 v96, v66
	v_mov_b32_e32 v97, v66
	v_mov_b32_e32 v106, v66
	v_mov_b32_e32 v107, v66
	v_mov_b32_e32 v108, v66
	v_mov_b32_e32 v109, v66
	v_mov_b32_e32 v110, v66
	v_mov_b32_e32 v111, v66
	v_mov_b32_e32 v112, v66
	v_mov_b32_e32 v113, v66
	v_mov_b32_e32 v122, v66
	v_mov_b32_e32 v123, v66
	v_mov_b32_e32 v124, v66
	v_mov_b32_e32 v125, v66
	v_mov_b32_e32 v126, v66
	v_mov_b32_e32 v127, v66
	v_mov_b32_e32 v128, v66
	v_mov_b32_e32 v129, v66
	v_mov_b32_e32 v130, v66
	v_mov_b32_e32 v131, v66
	v_mov_b32_e32 v132, v66
	v_mov_b32_e32 v133, v66
	v_mov_b32_e32 v134, v66
	v_mov_b32_e32 v135, v66
	v_mov_b32_e32 v136, v66
	v_mov_b32_e32 v137, v66
	v_mov_b32_e32 v146, v66
	v_mov_b32_e32 v147, v66
	v_mov_b32_e32 v148, v66
	v_mov_b32_e32 v149, v66
	v_mov_b32_e32 v150, v66
	v_mov_b32_e32 v151, v66
	v_mov_b32_e32 v152, v66
	v_mov_b32_e32 v153, v66
	v_mov_b32_e32 v162, v66
	v_mov_b32_e32 v163, v66
	v_mov_b32_e32 v164, v66
	v_mov_b32_e32 v165, v66
	v_mov_b32_e32 v166, v66
	v_mov_b32_e32 v167, v66
	v_mov_b32_e32 v168, v66
	v_mov_b32_e32 v169, v66
	v_mov_b32_e32 v178, v66
	v_mov_b32_e32 v179, v66
	v_mov_b32_e32 v180, v66
	v_mov_b32_e32 v181, v66
	v_mov_b32_e32 v182, v66
	v_mov_b32_e32 v183, v66
	v_mov_b32_e32 v184, v66
	v_mov_b32_e32 v185, v66
	v_mov_b32_e32 v138, v66
	v_mov_b32_e32 v139, v66
	v_mov_b32_e32 v140, v66
	v_mov_b32_e32 v141, v66
	v_mov_b32_e32 v142, v66
	v_mov_b32_e32 v143, v66
	v_mov_b32_e32 v144, v66
	v_mov_b32_e32 v145, v66
	v_mov_b32_e32 v154, v66
	v_mov_b32_e32 v155, v66
	v_mov_b32_e32 v156, v66
	v_mov_b32_e32 v157, v66
	v_mov_b32_e32 v158, v66
	v_mov_b32_e32 v159, v66
	v_mov_b32_e32 v160, v66
	v_mov_b32_e32 v161, v66
	v_mov_b32_e32 v170, v66
	v_mov_b32_e32 v171, v66
	v_mov_b32_e32 v172, v66
	v_mov_b32_e32 v173, v66
	v_mov_b32_e32 v174, v66
	v_mov_b32_e32 v175, v66
	v_mov_b32_e32 v176, v66
	v_mov_b32_e32 v177, v66
	v_mov_b32_e32 v186, v66
	v_mov_b32_e32 v187, v66
	v_mov_b32_e32 v188, v66
	v_mov_b32_e32 v189, v66
	v_mov_b32_e32 v190, v66
	v_mov_b32_e32 v191, v66
	v_mov_b32_e32 v192, v66
	v_mov_b32_e32 v193, v66
	s_branch .LBB0_251

.LBB0_1060:
	s_ashr_i32 s21, s20, 31
	s_lshl_b64 s[24:25], s[20:21], 19
	s_add_u32 s24, s45, s24
	s_addc_u32 s25, s46, s25
	s_and_b64 s[26:27], s[2:3], exec
	s_cselect_b32 s21, s25, s31
	s_cselect_b32 s73, s24, s30
	s_ashr_i32 s23, s22, 31
	s_lshl_b64 s[26:27], s[22:23], 19
	s_add_u32 s26, s47, s26
	s_addc_u32 s27, s48, s27
	s_and_b64 s[38:39], s[2:3], exec
	s_cselect_b32 s23, s27, s37
	s_cselect_b32 s74, s26, s36
	s_cmp_lg_u32 s34, 0
	s_cselect_b64 s[34:35], -1, 0
	s_add_u32 s75, s36, 0x100
	v_mov_b32_e32 v66, 0
	s_addc_u32 s76, s37, 0
	s_mov_b32 s77, -2
	s_mov_b64 s[36:37], 0
	v_mov_b32_e32 v67, v66
	v_mov_b32_e32 v68, v66
	v_mov_b32_e32 v69, v66
	v_mov_b32_e32 v70, v66
	v_mov_b32_e32 v71, v66
	v_mov_b32_e32 v72, v66
	v_mov_b32_e32 v73, v66
	v_mov_b32_e32 v78, v66
	v_mov_b32_e32 v79, v66
	v_mov_b32_e32 v80, v66
	v_mov_b32_e32 v81, v66
	v_mov_b32_e32 v86, v66
	v_mov_b32_e32 v87, v66
	v_mov_b32_e32 v88, v66
	v_mov_b32_e32 v89, v66
	v_mov_b32_e32 v94, v66
	v_mov_b32_e32 v95, v66
	v_mov_b32_e32 v96, v66
	v_mov_b32_e32 v97, v66
	v_mov_b32_e32 v102, v66
	v_mov_b32_e32 v103, v66
	v_mov_b32_e32 v104, v66
	v_mov_b32_e32 v105, v66
	v_mov_b32_e32 v110, v66
	v_mov_b32_e32 v111, v66
	v_mov_b32_e32 v112, v66
	v_mov_b32_e32 v113, v66
	v_mov_b32_e32 v118, v66
	v_mov_b32_e32 v119, v66
	v_mov_b32_e32 v120, v66
	v_mov_b32_e32 v121, v66
	v_mov_b32_e32 v74, v66
	v_mov_b32_e32 v75, v66
	v_mov_b32_e32 v76, v66
	v_mov_b32_e32 v77, v66
	v_mov_b32_e32 v82, v66
	v_mov_b32_e32 v83, v66
	v_mov_b32_e32 v84, v66
	v_mov_b32_e32 v85, v66
	v_mov_b32_e32 v90, v66
	v_mov_b32_e32 v91, v66
	v_mov_b32_e32 v92, v66
	v_mov_b32_e32 v93, v66
	v_mov_b32_e32 v98, v66
	v_mov_b32_e32 v99, v66
	v_mov_b32_e32 v100, v66
	v_mov_b32_e32 v101, v66
	v_mov_b32_e32 v106, v66
	v_mov_b32_e32 v107, v66
	v_mov_b32_e32 v108, v66
	v_mov_b32_e32 v109, v66
	v_mov_b32_e32 v114, v66
	v_mov_b32_e32 v115, v66
	v_mov_b32_e32 v116, v66
	v_mov_b32_e32 v117, v66
	v_mov_b32_e32 v122, v66
	v_mov_b32_e32 v123, v66
	v_mov_b32_e32 v124, v66
	v_mov_b32_e32 v125, v66
	v_mov_b32_e32 v126, v66
	v_mov_b32_e32 v127, v66
	v_mov_b32_e32 v128, v66
	v_mov_b32_e32 v129, v66
	v_mov_b32_e32 v130, v66
	v_mov_b32_e32 v131, v66
	v_mov_b32_e32 v132, v66
	v_mov_b32_e32 v133, v66
	v_mov_b32_e32 v134, v66
	v_mov_b32_e32 v135, v66
	v_mov_b32_e32 v136, v66
	v_mov_b32_e32 v137, v66
	v_mov_b32_e32 v142, v66
	v_mov_b32_e32 v143, v66
	v_mov_b32_e32 v144, v66
	v_mov_b32_e32 v145, v66
	v_mov_b32_e32 v150, v66
	v_mov_b32_e32 v151, v66
	v_mov_b32_e32 v152, v66
	v_mov_b32_e32 v153, v66
	v_mov_b32_e32 v158, v66
	v_mov_b32_e32 v159, v66
	v_mov_b32_e32 v160, v66
	v_mov_b32_e32 v161, v66
	v_mov_b32_e32 v166, v66
	v_mov_b32_e32 v167, v66
	v_mov_b32_e32 v168, v66
	v_mov_b32_e32 v169, v66
	v_mov_b32_e32 v174, v66
	v_mov_b32_e32 v175, v66
	v_mov_b32_e32 v176, v66
	v_mov_b32_e32 v177, v66
	v_mov_b32_e32 v182, v66
	v_mov_b32_e32 v183, v66
	v_mov_b32_e32 v184, v66
	v_mov_b32_e32 v185, v66
	v_mov_b32_e32 v138, v66
	v_mov_b32_e32 v139, v66
	v_mov_b32_e32 v140, v66
	v_mov_b32_e32 v141, v66
	v_mov_b32_e32 v146, v66
	v_mov_b32_e32 v147, v66
	v_mov_b32_e32 v148, v66
	v_mov_b32_e32 v149, v66
	v_mov_b32_e32 v154, v66
	v_mov_b32_e32 v155, v66
	v_mov_b32_e32 v156, v66
	v_mov_b32_e32 v157, v66
	v_mov_b32_e32 v162, v66
	v_mov_b32_e32 v163, v66
	v_mov_b32_e32 v164, v66
	v_mov_b32_e32 v165, v66
	v_mov_b32_e32 v170, v66
	v_mov_b32_e32 v171, v66
	v_mov_b32_e32 v172, v66
	v_mov_b32_e32 v173, v66
	v_mov_b32_e32 v178, v66
	v_mov_b32_e32 v179, v66
	v_mov_b32_e32 v180, v66
	v_mov_b32_e32 v181, v66
	v_mov_b32_e32 v186, v66
	v_mov_b32_e32 v187, v66
	v_mov_b32_e32 v188, v66
	v_mov_b32_e32 v189, v66
	v_mov_b32_e32 v190, v66
	v_mov_b32_e32 v191, v66
	v_mov_b32_e32 v192, v66
	v_mov_b32_e32 v193, v66
	s_branch .LBB0_1063

.LBB0_1223:
	s_ashr_i32 s35, s34, 31
	s_lshl_b64 s[38:39], s[34:35], 20
	s_add_u32 s38, s59, s38
	s_addc_u32 s39, s60, s39
	s_and_b64 s[40:41], s[14:15], exec
	s_cselect_b32 s35, s39, s47
	s_cselect_b32 s43, s38, s46
	s_ashr_i32 s37, s36, 31
	s_lshl_b64 s[40:41], s[36:37], 20
	s_add_u32 s40, s61, s40
	s_addc_u32 s41, s62, s41
	s_and_b64 s[52:53], s[14:15], exec
	s_cselect_b32 s37, s41, s51
	s_cselect_b32 s45, s40, s50
	s_cmp_lg_u32 s48, 0
	s_cselect_b64 s[48:49], -1, 0
	s_add_u32 s91, s50, 0x100
	v_mov_b32_e32 v2, 0
	s_addc_u32 s92, s51, 0
	s_mov_b32 s93, -2
	s_mov_b64 s[50:51], 0
	v_mov_b32_e32 v3, v2
	v_mov_b32_e32 v4, v2
	v_mov_b32_e32 v5, v2
	v_mov_b32_e32 v6, v2
	v_mov_b32_e32 v7, v2
	v_mov_b32_e32 v8, v2
	v_mov_b32_e32 v9, v2
	v_mov_b32_e32 v18, v2
	v_mov_b32_e32 v19, v2
	v_mov_b32_e32 v20, v2
	v_mov_b32_e32 v21, v2
	v_mov_b32_e32 v26, v2
	v_mov_b32_e32 v27, v2
	v_mov_b32_e32 v28, v2
	v_mov_b32_e32 v29, v2
	v_mov_b32_e32 v34, v2
	v_mov_b32_e32 v35, v2
	v_mov_b32_e32 v36, v2
	v_mov_b32_e32 v37, v2
	v_mov_b32_e32 v42, v2
	v_mov_b32_e32 v43, v2
	v_mov_b32_e32 v44, v2
	v_mov_b32_e32 v45, v2
	v_mov_b32_e32 v58, v2
	v_mov_b32_e32 v59, v2
	v_mov_b32_e32 v60, v2
	v_mov_b32_e32 v61, v2
	v_mov_b32_e32 v62, v2
	v_mov_b32_e32 v63, v2
	v_mov_b32_e32 v64, v2
	v_mov_b32_e32 v65, v2
	v_mov_b32_e32 v10, v2
	v_mov_b32_e32 v11, v2
	v_mov_b32_e32 v12, v2
	v_mov_b32_e32 v13, v2
	v_mov_b32_e32 v14, v2
	v_mov_b32_e32 v15, v2
	v_mov_b32_e32 v16, v2
	v_mov_b32_e32 v17, v2
	v_mov_b32_e32 v22, v2
	v_mov_b32_e32 v23, v2
	v_mov_b32_e32 v24, v2
	v_mov_b32_e32 v25, v2
	v_mov_b32_e32 v30, v2
	v_mov_b32_e32 v31, v2
	v_mov_b32_e32 v32, v2
	v_mov_b32_e32 v33, v2
	v_mov_b32_e32 v38, v2
	v_mov_b32_e32 v39, v2
	v_mov_b32_e32 v40, v2
	v_mov_b32_e32 v41, v2
	v_mov_b32_e32 v50, v2
	v_mov_b32_e32 v51, v2
	v_mov_b32_e32 v52, v2
	v_mov_b32_e32 v53, v2
	v_mov_b32_e32 v46, v2
	v_mov_b32_e32 v47, v2
	v_mov_b32_e32 v48, v2
	v_mov_b32_e32 v49, v2
	v_mov_b32_e32 v54, v2
	v_mov_b32_e32 v55, v2
	v_mov_b32_e32 v56, v2
	v_mov_b32_e32 v57, v2
	v_mov_b32_e32 v98, v2
	v_mov_b32_e32 v99, v2
	v_mov_b32_e32 v100, v2
	v_mov_b32_e32 v101, v2
	v_mov_b32_e32 v102, v2
	v_mov_b32_e32 v103, v2
	v_mov_b32_e32 v104, v2
	v_mov_b32_e32 v105, v2
	v_mov_b32_e32 v114, v2
	v_mov_b32_e32 v115, v2
	v_mov_b32_e32 v116, v2
	v_mov_b32_e32 v117, v2
	v_mov_b32_e32 v122, v2
	v_mov_b32_e32 v123, v2
	v_mov_b32_e32 v124, v2
	v_mov_b32_e32 v125, v2
	v_mov_b32_e32 v130, v2
	v_mov_b32_e32 v131, v2
	v_mov_b32_e32 v132, v2
	v_mov_b32_e32 v133, v2
	v_mov_b32_e32 v138, v2
	v_mov_b32_e32 v139, v2
	v_mov_b32_e32 v140, v2
	v_mov_b32_e32 v141, v2
	v_mov_b32_e32 v154, v2
	v_mov_b32_e32 v155, v2
	v_mov_b32_e32 v156, v2
	v_mov_b32_e32 v157, v2
	v_mov_b32_e32 v158, v2
	v_mov_b32_e32 v159, v2
	v_mov_b32_e32 v160, v2
	v_mov_b32_e32 v161, v2
	v_mov_b32_e32 v106, v2
	v_mov_b32_e32 v107, v2
	v_mov_b32_e32 v108, v2
	v_mov_b32_e32 v109, v2
	v_mov_b32_e32 v110, v2
	v_mov_b32_e32 v111, v2
	v_mov_b32_e32 v112, v2
	v_mov_b32_e32 v113, v2
	v_mov_b32_e32 v118, v2
	v_mov_b32_e32 v119, v2
	v_mov_b32_e32 v120, v2
	v_mov_b32_e32 v121, v2
	v_mov_b32_e32 v126, v2
	v_mov_b32_e32 v127, v2
	v_mov_b32_e32 v128, v2
	v_mov_b32_e32 v129, v2
	v_mov_b32_e32 v134, v2
	v_mov_b32_e32 v135, v2
	v_mov_b32_e32 v136, v2
	v_mov_b32_e32 v137, v2
	v_mov_b32_e32 v146, v2
	v_mov_b32_e32 v147, v2
	v_mov_b32_e32 v148, v2
	v_mov_b32_e32 v149, v2
	v_mov_b32_e32 v142, v2
	v_mov_b32_e32 v143, v2
	v_mov_b32_e32 v144, v2
	v_mov_b32_e32 v145, v2
	v_mov_b32_e32 v150, v2
	v_mov_b32_e32 v151, v2
	v_mov_b32_e32 v152, v2
	v_mov_b32_e32 v153, v2
	s_branch .LBB0_1226

.LBB0_1395:
	s_cmp_lg_u32 s24, 0
	s_cselect_b64 s[24:25], -1, 0
	s_add_u32 s70, s26, 0x100
	v_mov_b32_e32 v2, 0
	s_addc_u32 s71, s27, 0
	s_mov_b32 s72, -2
	s_mov_b64 s[26:27], 0
	v_mov_b32_e32 v3, v2
	v_mov_b32_e32 v4, v2
	v_mov_b32_e32 v5, v2
	v_mov_b32_e32 v6, v2
	v_mov_b32_e32 v7, v2
	v_mov_b32_e32 v8, v2
	v_mov_b32_e32 v9, v2
	v_mov_b32_e32 v10, v2
	v_mov_b32_e32 v11, v2
	v_mov_b32_e32 v12, v2
	v_mov_b32_e32 v13, v2
	v_mov_b32_e32 v18, v2
	v_mov_b32_e32 v19, v2
	v_mov_b32_e32 v20, v2
	v_mov_b32_e32 v21, v2
	v_mov_b32_e32 v26, v2
	v_mov_b32_e32 v27, v2
	v_mov_b32_e32 v28, v2
	v_mov_b32_e32 v29, v2
	v_mov_b32_e32 v34, v2
	v_mov_b32_e32 v35, v2
	v_mov_b32_e32 v36, v2
	v_mov_b32_e32 v37, v2
	v_mov_b32_e32 v42, v2
	v_mov_b32_e32 v43, v2
	v_mov_b32_e32 v44, v2
	v_mov_b32_e32 v45, v2
	v_mov_b32_e32 v50, v2
	v_mov_b32_e32 v51, v2
	v_mov_b32_e32 v52, v2
	v_mov_b32_e32 v53, v2
	v_mov_b32_e32 v14, v2
	v_mov_b32_e32 v15, v2
	v_mov_b32_e32 v16, v2
	v_mov_b32_e32 v17, v2
	v_mov_b32_e32 v22, v2
	v_mov_b32_e32 v23, v2
	v_mov_b32_e32 v24, v2
	v_mov_b32_e32 v25, v2
	v_mov_b32_e32 v30, v2
	v_mov_b32_e32 v31, v2
	v_mov_b32_e32 v32, v2
	v_mov_b32_e32 v33, v2
	v_mov_b32_e32 v38, v2
	v_mov_b32_e32 v39, v2
	v_mov_b32_e32 v40, v2
	v_mov_b32_e32 v41, v2
	v_mov_b32_e32 v46, v2
	v_mov_b32_e32 v47, v2
	v_mov_b32_e32 v48, v2
	v_mov_b32_e32 v49, v2
	v_mov_b32_e32 v54, v2
	v_mov_b32_e32 v55, v2
	v_mov_b32_e32 v56, v2
	v_mov_b32_e32 v57, v2
	v_mov_b32_e32 v58, v2
	v_mov_b32_e32 v59, v2
	v_mov_b32_e32 v60, v2
	v_mov_b32_e32 v61, v2
	v_mov_b32_e32 v62, v2
	v_mov_b32_e32 v63, v2
	v_mov_b32_e32 v64, v2
	v_mov_b32_e32 v65, v2
	v_mov_b32_e32 v66, v2
	v_mov_b32_e32 v67, v2
	v_mov_b32_e32 v68, v2
	v_mov_b32_e32 v69, v2
	v_mov_b32_e32 v70, v2
	v_mov_b32_e32 v71, v2
	v_mov_b32_e32 v72, v2
	v_mov_b32_e32 v73, v2
	v_mov_b32_e32 v74, v2
	v_mov_b32_e32 v75, v2
	v_mov_b32_e32 v76, v2
	v_mov_b32_e32 v77, v2
	v_mov_b32_e32 v82, v2
	v_mov_b32_e32 v83, v2
	v_mov_b32_e32 v84, v2
	v_mov_b32_e32 v85, v2
	v_mov_b32_e32 v90, v2
	v_mov_b32_e32 v91, v2
	v_mov_b32_e32 v92, v2
	v_mov_b32_e32 v93, v2
	v_mov_b32_e32 v98, v2
	v_mov_b32_e32 v99, v2
	v_mov_b32_e32 v100, v2
	v_mov_b32_e32 v101, v2
	v_mov_b32_e32 v106, v2
	v_mov_b32_e32 v107, v2
	v_mov_b32_e32 v108, v2
	v_mov_b32_e32 v109, v2
	v_mov_b32_e32 v114, v2
	v_mov_b32_e32 v115, v2
	v_mov_b32_e32 v116, v2
	v_mov_b32_e32 v117, v2
	v_mov_b32_e32 v78, v2
	v_mov_b32_e32 v79, v2
	v_mov_b32_e32 v80, v2
	v_mov_b32_e32 v81, v2
	v_mov_b32_e32 v86, v2
	v_mov_b32_e32 v87, v2
	v_mov_b32_e32 v88, v2
	v_mov_b32_e32 v89, v2
	v_mov_b32_e32 v94, v2
	v_mov_b32_e32 v95, v2
	v_mov_b32_e32 v96, v2
	v_mov_b32_e32 v97, v2
	v_mov_b32_e32 v102, v2
	v_mov_b32_e32 v103, v2
	v_mov_b32_e32 v104, v2
	v_mov_b32_e32 v105, v2
	v_mov_b32_e32 v110, v2
	v_mov_b32_e32 v111, v2
	v_mov_b32_e32 v112, v2
	v_mov_b32_e32 v113, v2
	v_mov_b32_e32 v118, v2
	v_mov_b32_e32 v119, v2
	v_mov_b32_e32 v120, v2
	v_mov_b32_e32 v121, v2
	v_mov_b32_e32 v122, v2
	v_mov_b32_e32 v123, v2
	v_mov_b32_e32 v124, v2
	v_mov_b32_e32 v125, v2
	v_mov_b32_e32 v126, v2
	v_mov_b32_e32 v127, v2
	v_mov_b32_e32 v128, v2
	v_mov_b32_e32 v129, v2
	s_branch .LBB0_1398

.LBB0_2407:
	s_ashr_i32 s21, s20, 31
	s_lshl_b64 s[24:25], s[20:21], 19
	s_add_u32 s24, s46, s24
	s_addc_u32 s25, s47, s25
	s_and_b64 s[26:27], s[2:3], exec
	s_cselect_b32 s21, s25, s31
	s_cselect_b32 s72, s24, s30
	s_ashr_i32 s23, s22, 31
	s_lshl_b64 s[26:27], s[22:23], 19
	s_add_u32 s26, s48, s26
	s_addc_u32 s27, s49, s27
	s_and_b64 s[38:39], s[2:3], exec
	s_cselect_b32 s23, s27, s37
	s_cselect_b32 s73, s26, s36
	s_cmp_lg_u32 s34, 0
	s_cselect_b64 s[34:35], -1, 0
	s_add_u32 s74, s36, 0x100
	v_mov_b32_e32 v66, 0
	s_addc_u32 s75, s37, 0
	s_mov_b32 s76, -2
	s_mov_b64 s[36:37], 0
	v_mov_b32_e32 v67, v66
	v_mov_b32_e32 v68, v66
	v_mov_b32_e32 v69, v66
	v_mov_b32_e32 v70, v66
	v_mov_b32_e32 v71, v66
	v_mov_b32_e32 v72, v66
	v_mov_b32_e32 v73, v66
	v_mov_b32_e32 v78, v66
	v_mov_b32_e32 v79, v66
	v_mov_b32_e32 v80, v66
	v_mov_b32_e32 v81, v66
	v_mov_b32_e32 v86, v66
	v_mov_b32_e32 v87, v66
	v_mov_b32_e32 v88, v66
	v_mov_b32_e32 v89, v66
	v_mov_b32_e32 v94, v66
	v_mov_b32_e32 v95, v66
	v_mov_b32_e32 v96, v66
	v_mov_b32_e32 v97, v66
	v_mov_b32_e32 v102, v66
	v_mov_b32_e32 v103, v66
	v_mov_b32_e32 v104, v66
	v_mov_b32_e32 v105, v66
	v_mov_b32_e32 v110, v66
	v_mov_b32_e32 v111, v66
	v_mov_b32_e32 v112, v66
	v_mov_b32_e32 v113, v66
	v_mov_b32_e32 v118, v66
	v_mov_b32_e32 v119, v66
	v_mov_b32_e32 v120, v66
	v_mov_b32_e32 v121, v66
	v_mov_b32_e32 v74, v66
	v_mov_b32_e32 v75, v66
	v_mov_b32_e32 v76, v66
	v_mov_b32_e32 v77, v66
	v_mov_b32_e32 v82, v66
	v_mov_b32_e32 v83, v66
	v_mov_b32_e32 v84, v66
	v_mov_b32_e32 v85, v66
	v_mov_b32_e32 v90, v66
	v_mov_b32_e32 v91, v66
	v_mov_b32_e32 v92, v66
	v_mov_b32_e32 v93, v66
	v_mov_b32_e32 v98, v66
	v_mov_b32_e32 v99, v66
	v_mov_b32_e32 v100, v66
	v_mov_b32_e32 v101, v66
	v_mov_b32_e32 v106, v66
	v_mov_b32_e32 v107, v66
	v_mov_b32_e32 v108, v66
	v_mov_b32_e32 v109, v66
	v_mov_b32_e32 v114, v66
	v_mov_b32_e32 v115, v66
	v_mov_b32_e32 v116, v66
	v_mov_b32_e32 v117, v66
	v_mov_b32_e32 v122, v66
	v_mov_b32_e32 v123, v66
	v_mov_b32_e32 v124, v66
	v_mov_b32_e32 v125, v66
	v_mov_b32_e32 v126, v66
	v_mov_b32_e32 v127, v66
	v_mov_b32_e32 v128, v66
	v_mov_b32_e32 v129, v66
	v_mov_b32_e32 v130, v66
	v_mov_b32_e32 v131, v66
	v_mov_b32_e32 v132, v66
	v_mov_b32_e32 v133, v66
	v_mov_b32_e32 v134, v66
	v_mov_b32_e32 v135, v66
	v_mov_b32_e32 v136, v66
	v_mov_b32_e32 v137, v66
	v_mov_b32_e32 v142, v66
	v_mov_b32_e32 v143, v66
	v_mov_b32_e32 v144, v66
	v_mov_b32_e32 v145, v66
	v_mov_b32_e32 v150, v66
	v_mov_b32_e32 v151, v66
	v_mov_b32_e32 v152, v66
	v_mov_b32_e32 v153, v66
	v_mov_b32_e32 v158, v66
	v_mov_b32_e32 v159, v66
	v_mov_b32_e32 v160, v66
	v_mov_b32_e32 v161, v66
	v_mov_b32_e32 v166, v66
	v_mov_b32_e32 v167, v66
	v_mov_b32_e32 v168, v66
	v_mov_b32_e32 v169, v66
	v_mov_b32_e32 v174, v66
	v_mov_b32_e32 v175, v66
	v_mov_b32_e32 v176, v66
	v_mov_b32_e32 v177, v66
	v_mov_b32_e32 v182, v66
	v_mov_b32_e32 v183, v66
	v_mov_b32_e32 v184, v66
	v_mov_b32_e32 v185, v66
	v_mov_b32_e32 v138, v66
	v_mov_b32_e32 v139, v66
	v_mov_b32_e32 v140, v66
	v_mov_b32_e32 v141, v66
	v_mov_b32_e32 v146, v66
	v_mov_b32_e32 v147, v66
	v_mov_b32_e32 v148, v66
	v_mov_b32_e32 v149, v66
	v_mov_b32_e32 v154, v66
	v_mov_b32_e32 v155, v66
	v_mov_b32_e32 v156, v66
	v_mov_b32_e32 v157, v66
	v_mov_b32_e32 v162, v66
	v_mov_b32_e32 v163, v66
	v_mov_b32_e32 v164, v66
	v_mov_b32_e32 v165, v66
	v_mov_b32_e32 v170, v66
	v_mov_b32_e32 v171, v66
	v_mov_b32_e32 v172, v66
	v_mov_b32_e32 v173, v66
	v_mov_b32_e32 v178, v66
	v_mov_b32_e32 v179, v66
	v_mov_b32_e32 v180, v66
	v_mov_b32_e32 v181, v66
	v_mov_b32_e32 v186, v66
	v_mov_b32_e32 v187, v66
	v_mov_b32_e32 v188, v66
	v_mov_b32_e32 v189, v66
	v_mov_b32_e32 v190, v66
	v_mov_b32_e32 v191, v66
	v_mov_b32_e32 v192, v66
	v_mov_b32_e32 v193, v66
	s_branch .LBB0_2410

.LBB0_2557:
	s_ashr_i32 s35, s34, 31
	s_lshl_b64 s[38:39], s[34:35], 20
	s_add_u32 s38, s59, s38
	s_addc_u32 s39, s60, s39
	s_and_b64 s[40:41], s[14:15], exec
	s_cselect_b32 s35, s39, s47
	s_cselect_b32 s43, s38, s46
	s_ashr_i32 s37, s36, 31
	s_lshl_b64 s[40:41], s[36:37], 20
	s_add_u32 s40, s61, s40
	s_addc_u32 s41, s62, s41
	s_and_b64 s[52:53], s[14:15], exec
	s_cselect_b32 s37, s41, s51
	s_cselect_b32 s45, s40, s50
	s_cmp_lg_u32 s48, 0
	s_cselect_b64 s[48:49], -1, 0
	s_add_u32 s91, s50, 0x100
	v_mov_b32_e32 v2, 0
	s_addc_u32 s92, s51, 0
	s_mov_b32 s93, -2
	s_mov_b64 s[50:51], 0
	v_mov_b32_e32 v3, v2
	v_mov_b32_e32 v4, v2
	v_mov_b32_e32 v5, v2
	v_mov_b32_e32 v6, v2
	v_mov_b32_e32 v7, v2
	v_mov_b32_e32 v8, v2
	v_mov_b32_e32 v9, v2
	v_mov_b32_e32 v18, v2
	v_mov_b32_e32 v19, v2
	v_mov_b32_e32 v20, v2
	v_mov_b32_e32 v21, v2
	v_mov_b32_e32 v26, v2
	v_mov_b32_e32 v27, v2
	v_mov_b32_e32 v28, v2
	v_mov_b32_e32 v29, v2
	v_mov_b32_e32 v34, v2
	v_mov_b32_e32 v35, v2
	v_mov_b32_e32 v36, v2
	v_mov_b32_e32 v37, v2
	v_mov_b32_e32 v42, v2
	v_mov_b32_e32 v43, v2
	v_mov_b32_e32 v44, v2
	v_mov_b32_e32 v45, v2
	v_mov_b32_e32 v58, v2
	v_mov_b32_e32 v59, v2
	v_mov_b32_e32 v60, v2
	v_mov_b32_e32 v61, v2
	v_mov_b32_e32 v62, v2
	v_mov_b32_e32 v63, v2
	v_mov_b32_e32 v64, v2
	v_mov_b32_e32 v65, v2
	v_mov_b32_e32 v10, v2
	v_mov_b32_e32 v11, v2
	v_mov_b32_e32 v12, v2
	v_mov_b32_e32 v13, v2
	v_mov_b32_e32 v14, v2
	v_mov_b32_e32 v15, v2
	v_mov_b32_e32 v16, v2
	v_mov_b32_e32 v17, v2
	v_mov_b32_e32 v22, v2
	v_mov_b32_e32 v23, v2
	v_mov_b32_e32 v24, v2
	v_mov_b32_e32 v25, v2
	v_mov_b32_e32 v30, v2
	v_mov_b32_e32 v31, v2
	v_mov_b32_e32 v32, v2
	v_mov_b32_e32 v33, v2
	v_mov_b32_e32 v38, v2
	v_mov_b32_e32 v39, v2
	v_mov_b32_e32 v40, v2
	v_mov_b32_e32 v41, v2
	v_mov_b32_e32 v50, v2
	v_mov_b32_e32 v51, v2
	v_mov_b32_e32 v52, v2
	v_mov_b32_e32 v53, v2
	v_mov_b32_e32 v46, v2
	v_mov_b32_e32 v47, v2
	v_mov_b32_e32 v48, v2
	v_mov_b32_e32 v49, v2
	v_mov_b32_e32 v54, v2
	v_mov_b32_e32 v55, v2
	v_mov_b32_e32 v56, v2
	v_mov_b32_e32 v57, v2
	s_waitcnt vmcnt(0)
	v_mov_b32_e32 v98, v2
	v_mov_b32_e32 v99, v2
	v_mov_b32_e32 v100, v2
	v_mov_b32_e32 v101, v2
	v_mov_b32_e32 v102, v2
	v_mov_b32_e32 v103, v2
	v_mov_b32_e32 v104, v2
	v_mov_b32_e32 v105, v2
	v_mov_b32_e32 v114, v2
	v_mov_b32_e32 v115, v2
	v_mov_b32_e32 v116, v2
	v_mov_b32_e32 v117, v2
	v_mov_b32_e32 v122, v2
	v_mov_b32_e32 v123, v2
	v_mov_b32_e32 v124, v2
	v_mov_b32_e32 v125, v2
	v_mov_b32_e32 v130, v2
	v_mov_b32_e32 v131, v2
	v_mov_b32_e32 v132, v2
	v_mov_b32_e32 v133, v2
	v_mov_b32_e32 v138, v2
	v_mov_b32_e32 v139, v2
	v_mov_b32_e32 v140, v2
	v_mov_b32_e32 v141, v2
	v_mov_b32_e32 v154, v2
	v_mov_b32_e32 v155, v2
	v_mov_b32_e32 v156, v2
	v_mov_b32_e32 v157, v2
	v_mov_b32_e32 v158, v2
	v_mov_b32_e32 v159, v2
	v_mov_b32_e32 v160, v2
	v_mov_b32_e32 v161, v2
	v_mov_b32_e32 v106, v2
	v_mov_b32_e32 v107, v2
	v_mov_b32_e32 v108, v2
	v_mov_b32_e32 v109, v2
	v_mov_b32_e32 v110, v2
	v_mov_b32_e32 v111, v2
	v_mov_b32_e32 v112, v2
	v_mov_b32_e32 v113, v2
	v_mov_b32_e32 v118, v2
	v_mov_b32_e32 v119, v2
	v_mov_b32_e32 v120, v2
	v_mov_b32_e32 v121, v2
	v_mov_b32_e32 v126, v2
	v_mov_b32_e32 v127, v2
	v_mov_b32_e32 v128, v2
	v_mov_b32_e32 v129, v2
	v_mov_b32_e32 v134, v2
	v_mov_b32_e32 v135, v2
	v_mov_b32_e32 v136, v2
	v_mov_b32_e32 v137, v2
	v_mov_b32_e32 v146, v2
	v_mov_b32_e32 v147, v2
	v_mov_b32_e32 v148, v2
	v_mov_b32_e32 v149, v2
	v_mov_b32_e32 v142, v2
	v_mov_b32_e32 v143, v2
	v_mov_b32_e32 v144, v2
	v_mov_b32_e32 v145, v2
	v_mov_b32_e32 v150, v2
	v_mov_b32_e32 v151, v2
	v_mov_b32_e32 v152, v2
	v_mov_b32_e32 v153, v2
	s_branch .LBB0_2560

.LBB0_2739:
	s_cmp_lg_u32 s24, 0
	s_cselect_b64 s[24:25], -1, 0
	s_add_u32 s67, s26, 0x100
	v_mov_b32_e32 v2, 0
	s_addc_u32 s68, s27, 0
	s_mov_b32 s69, -2
	s_mov_b64 s[26:27], 0
	v_mov_b32_e32 v3, v2
	v_mov_b32_e32 v4, v2
	v_mov_b32_e32 v5, v2
	v_mov_b32_e32 v6, v2
	v_mov_b32_e32 v7, v2
	v_mov_b32_e32 v8, v2
	v_mov_b32_e32 v9, v2
	v_mov_b32_e32 v10, v2
	v_mov_b32_e32 v11, v2
	v_mov_b32_e32 v12, v2
	v_mov_b32_e32 v13, v2
	v_mov_b32_e32 v18, v2
	v_mov_b32_e32 v19, v2
	v_mov_b32_e32 v20, v2
	v_mov_b32_e32 v21, v2
	v_mov_b32_e32 v26, v2
	v_mov_b32_e32 v27, v2
	v_mov_b32_e32 v28, v2
	v_mov_b32_e32 v29, v2
	v_mov_b32_e32 v34, v2
	v_mov_b32_e32 v35, v2
	v_mov_b32_e32 v36, v2
	v_mov_b32_e32 v37, v2
	v_mov_b32_e32 v42, v2
	v_mov_b32_e32 v43, v2
	v_mov_b32_e32 v44, v2
	v_mov_b32_e32 v45, v2
	v_mov_b32_e32 v50, v2
	v_mov_b32_e32 v51, v2
	v_mov_b32_e32 v52, v2
	v_mov_b32_e32 v53, v2
	v_mov_b32_e32 v14, v2
	v_mov_b32_e32 v15, v2
	v_mov_b32_e32 v16, v2
	v_mov_b32_e32 v17, v2
	v_mov_b32_e32 v22, v2
	v_mov_b32_e32 v23, v2
	v_mov_b32_e32 v24, v2
	v_mov_b32_e32 v25, v2
	v_mov_b32_e32 v30, v2
	v_mov_b32_e32 v31, v2
	v_mov_b32_e32 v32, v2
	v_mov_b32_e32 v33, v2
	v_mov_b32_e32 v38, v2
	v_mov_b32_e32 v39, v2
	v_mov_b32_e32 v40, v2
	v_mov_b32_e32 v41, v2
	v_mov_b32_e32 v46, v2
	v_mov_b32_e32 v47, v2
	v_mov_b32_e32 v48, v2
	v_mov_b32_e32 v49, v2
	v_mov_b32_e32 v54, v2
	v_mov_b32_e32 v55, v2
	v_mov_b32_e32 v56, v2
	v_mov_b32_e32 v57, v2
	v_mov_b32_e32 v58, v2
	v_mov_b32_e32 v59, v2
	v_mov_b32_e32 v60, v2
	v_mov_b32_e32 v61, v2
	v_mov_b32_e32 v62, v2
	v_mov_b32_e32 v63, v2
	v_mov_b32_e32 v64, v2
	v_mov_b32_e32 v65, v2
	v_mov_b32_e32 v66, v2
	v_mov_b32_e32 v67, v2
	v_mov_b32_e32 v68, v2
	v_mov_b32_e32 v69, v2
	v_mov_b32_e32 v70, v2
	v_mov_b32_e32 v71, v2
	v_mov_b32_e32 v72, v2
	v_mov_b32_e32 v73, v2
	v_mov_b32_e32 v74, v2
	v_mov_b32_e32 v75, v2
	v_mov_b32_e32 v76, v2
	v_mov_b32_e32 v77, v2
	v_mov_b32_e32 v82, v2
	v_mov_b32_e32 v83, v2
	v_mov_b32_e32 v84, v2
	v_mov_b32_e32 v85, v2
	v_mov_b32_e32 v90, v2
	v_mov_b32_e32 v91, v2
	v_mov_b32_e32 v92, v2
	v_mov_b32_e32 v93, v2
	v_mov_b32_e32 v98, v2
	v_mov_b32_e32 v99, v2
	v_mov_b32_e32 v100, v2
	v_mov_b32_e32 v101, v2
	v_mov_b32_e32 v106, v2
	v_mov_b32_e32 v107, v2
	v_mov_b32_e32 v108, v2
	v_mov_b32_e32 v109, v2
	v_mov_b32_e32 v114, v2
	v_mov_b32_e32 v115, v2
	v_mov_b32_e32 v116, v2
	v_mov_b32_e32 v117, v2
	v_mov_b32_e32 v78, v2
	v_mov_b32_e32 v79, v2
	v_mov_b32_e32 v80, v2
	v_mov_b32_e32 v81, v2
	v_mov_b32_e32 v86, v2
	v_mov_b32_e32 v87, v2
	v_mov_b32_e32 v88, v2
	v_mov_b32_e32 v89, v2
	v_mov_b32_e32 v94, v2
	v_mov_b32_e32 v95, v2
	v_mov_b32_e32 v96, v2
	v_mov_b32_e32 v97, v2
	v_mov_b32_e32 v102, v2
	v_mov_b32_e32 v103, v2
	v_mov_b32_e32 v104, v2
	v_mov_b32_e32 v105, v2
	v_mov_b32_e32 v110, v2
	v_mov_b32_e32 v111, v2
	v_mov_b32_e32 v112, v2
	v_mov_b32_e32 v113, v2
	v_mov_b32_e32 v118, v2
	v_mov_b32_e32 v119, v2
	v_mov_b32_e32 v120, v2
	v_mov_b32_e32 v121, v2
	v_mov_b32_e32 v122, v2
	v_mov_b32_e32 v123, v2
	v_mov_b32_e32 v124, v2
	v_mov_b32_e32 v125, v2
	v_mov_b32_e32 v126, v2
	v_mov_b32_e32 v127, v2
	v_mov_b32_e32 v128, v2
	v_mov_b32_e32 v129, v2
	s_branch .LBB0_2742
